# sample-stream attention computed directly (16 query rows per unit) instead of padded 256x256 score and P@V tiles; prompt units two per workgroup
# baseline (speedup 1.0000x reference)
;     __device__ bool next(int i, Unit& u) const { const int nr = nwg / G; if (i >= nr) return false; return RegSched::next(nr - 1 - i, u); }
;     __device__ bool next(int i, Unit& u) const {
;         int L;
;         if (skip) L = i * G + c + skip;
;         else if (G == 256) { if (c < 64) L = (i == 0) ? c : (i == 1 ? 512 + c : 1 << 20); else L = c + 192 * i; if (c >= 64 && L >= 512) L = 1 << 20; }
;         else L = i * G + c;
;         if (L >= 512 + 64) return false;
.LBB0_1013:
	s_and_b64 vcc, exec, s[8:9]
	s_mov_b32 s1, s7
	s_cbranch_vccnz .LBB0_1017
	v_readlane_b32 s40, v254, 61
	v_readlane_b32 s41, v254, 62
	s_and_b64 vcc, exec, s[40:41]
	s_add_i32 s1, s2, 0x100
	s_nop 0
	s_cmp_eq_u32 s79, 0
	s_cselect_b32 s1, s1, 0x100000

; #define LAS __attribute__((address_space(3)))
; #define EPI_FOR_ROWS for (int ai = 0; ai < 2; ++ai) _Pragma("unroll") for (int m = 0; m < 4; ++m)
;     __device__ __forceinline__ void operator()(f32x4 (&acc)[2][2][4][2], const Unit& u, int wr, int wc, int fr_, int fq_, LAS unsigned char* ldsx) const {
;         int fr = fr_, fq = fq_; asm volatile("" : "+v"(fr), "+v"(fq));
;         LAS f32x2* X = (LAS f32x2*)ldsx;
;         float mx[2][4];
; #pragma unroll
;         EPI_FOR_ROWS {
;             float mv = -3.0e38f;
; #pragma unroll
;             for (int bj = 0; bj < 2; ++bj)
; #pragma unroll
;                 for (int n = 0; n < 2; ++n)
; #pragma unroll
;                     for (int e = 0; e < 4; ++e) mv = fmaxf(mv, acc[ai][bj][m][n][e]);
;             mv = fmaxf(mv, __shfl_xor(mv, 16)); mv = fmaxf(mv, __shfl_xor(mv, 32));
;             float s = 0.f;
; #pragma unroll
;             for (int bj = 0; bj < 2; ++bj)
; #pragma unroll
;                 for (int n = 0; n < 2; ++n)
; #pragma unroll
;                     for (int e = 0; e < 4; ++e) { const float pe = __expf(acc[ai][bj][m][n][e] - mv); acc[ai][bj][m][n][e] = pe; s += pe; }
;             s += __shfl_xor(s, 16); s += __shfl_xor(s, 32);
;             mx[ai][m] = mv;
;             if (fq == 0) X[(ai * HALF + wr * 64 + m * 16 + fr) * 4 + wc] = (f32x2){mv, s};
; __global__ void __launch_bounds__(512, 2) fwd_megakernel(Params p) {
;     ...
;     asm volatile("s_waitcnt vmcnt(0)" ::: "memory"); __syncthreads();
;     if (F.tid == 0) { __builtin_amdgcn_fence(__ATOMIC_ACQUIRE, "agent"); asm volatile("s_waitcnt vmcnt(0)" ::: "memory"); }
;     __syncthreads();
;     if constexpr (PHASE_MASK & 1024) { AttSched S{Pb, Vt, 1, G, c, 512}; EpiGen<0> E{Ob, DM, nullptr, 0, nullptr, 1.f};
;       gemm_phase<EpiGen<0>, AttSched, true>(F.lds, GemmDesc{NMEM, DM, NMEM}, S, E); }
.LBB0_1094:
	s_or_b64 exec, exec, s[0:1]
	v_mov_b32_e32 v8, v202
	s_cmpk_lt_i32 s3, 0x240
	s_barrier
	s_cmp_lt_u32 s2, 64
	s_cbranch_scc0 .Lsat_done
	s_lshr_b32 s4, s2, 2
	s_and_b32 s5, s2, 3
	v_readfirstlane_b32 s6, v202
	s_lshr_b32 s6, s6, 6
	v_and_b32_e32 v180, 63, v202
	v_and_b32_e32 v181, 15, v180
	v_lshrrev_b32_e32 v182, 4, v180
	s_lshl_b32 s7, s4, 15
	s_lshl_b32 s8, s5, 9
	s_add_i32 s9, s7, s8
	s_add_i32 s10, s9, 0xfc00000
	s_add_i32 s11, s9, 0x18000000
	s_lshl_b32 s12, s6, 6
	s_add_i32 s11, s11, s12
	s_lshl_b32 s13, s4, 19
	s_add_i32 s13, s13, 0x100000
	s_add_i32 s16, s13, s8
	s_lshl_b32 s17, s6, 16
	s_add_i32 s16, s16, s17
	s_add_i32 s16, s16, 0x2400000
	s_lshl_b32 s17, s5, 17
	s_add_i32 s17, s17, s13
	s_lshl_b32 s18, s6, 14
	s_add_i32 s17, s17, s18
	s_add_i32 s17, s17, 0x2d00000
	v_lshlrev_b32_e32 v183, 4, v182
	v_lshl_add_u32 v184, v181, 11, v183
	v_add_u32_e32 v185, s10, v184
	v_lshrrev_b32_e32 v197, 2, v181
	v_and_b32_e32 v200, 3, v181
	v_lshl_add_u32 v197, v197, 3, v200
	v_lshl_add_u32 v197, v197, 11, v183
	v_add_u32_e32 v186, s16, v197
	v_add_u32_e32 v187, 0x2000, v186
	v_lshl_add_u32 v197, v181, 9, v183
	v_add_u32_e32 v188, s17, v197
	v_add_u32_e32 v189, 0x2000, v188
	v_lshlrev_b32_e32 v197, 3, v182
	v_lshl_add_u32 v197, v181, 11, v197
	v_add_u32_e32 v190, s11, v197
	global_load_dwordx4 v[20:23], v185, s[58:59]
	global_load_dwordx4 v[24:27], v185, s[58:59] offset:64
	global_load_dwordx4 v[28:31], v185, s[58:59] offset:128
	global_load_dwordx4 v[32:35], v185, s[58:59] offset:192
	global_load_dwordx4 v[36:39], v185, s[58:59] offset:256
	global_load_dwordx4 v[40:43], v185, s[58:59] offset:320
	global_load_dwordx4 v[44:47], v185, s[58:59] offset:384
	global_load_dwordx4 v[48:51], v185, s[58:59] offset:448
	global_load_dwordx4 v[52:55], v186, s[58:59]
	global_load_dwordx4 v[56:59], v186, s[58:59] offset:64
	global_load_dwordx4 v[60:63], v186, s[58:59] offset:128
	global_load_dwordx4 v[64:67], v186, s[58:59] offset:192
	global_load_dwordx4 v[68:71], v186, s[58:59] offset:256
	global_load_dwordx4 v[72:75], v186, s[58:59] offset:320
	global_load_dwordx4 v[76:79], v186, s[58:59] offset:384
	global_load_dwordx4 v[80:83], v186, s[58:59] offset:448
	global_load_dwordx4 v[84:87], v187, s[58:59]
	global_load_dwordx4 v[88:91], v187, s[58:59] offset:64
	global_load_dwordx4 v[92:95], v187, s[58:59] offset:128
	global_load_dwordx4 v[96:99], v187, s[58:59] offset:192
	global_load_dwordx4 v[100:103], v187, s[58:59] offset:256
	global_load_dwordx4 v[104:107], v187, s[58:59] offset:320
	global_load_dwordx4 v[108:111], v187, s[58:59] offset:384
	global_load_dwordx4 v[112:115], v187, s[58:59] offset:448
	global_load_dwordx4 v[116:119], v188, s[58:59]
	global_load_dwordx4 v[120:123], v188, s[58:59] offset:64
	global_load_dwordx4 v[124:127], v188, s[58:59] offset:128
	global_load_dwordx4 v[128:131], v188, s[58:59] offset:192
	global_load_dwordx4 v[132:135], v188, s[58:59] offset:256
	global_load_dwordx4 v[136:139], v188, s[58:59] offset:320
	global_load_dwordx4 v[140:143], v188, s[58:59] offset:384
	global_load_dwordx4 v[144:147], v188, s[58:59] offset:448
	global_load_dwordx4 v[148:151], v189, s[58:59]
	global_load_dwordx4 v[152:155], v189, s[58:59] offset:64
	global_load_dwordx4 v[156:159], v189, s[58:59] offset:128
	global_load_dwordx4 v[160:163], v189, s[58:59] offset:192
	global_load_dwordx4 v[164:167], v189, s[58:59] offset:256
	global_load_dwordx4 v[168:171], v189, s[58:59] offset:320
	global_load_dwordx4 v[172:175], v189, s[58:59] offset:384
	global_load_dwordx4 v[176:179], v189, s[58:59] offset:448
	v_xor_b32_e32 v191, 16, v180
	v_lshlrev_b32_e32 v191, 2, v191
	v_xor_b32_e32 v192, 32, v180
	v_lshlrev_b32_e32 v192, 2, v192
	v_lshlrev_b32_e32 v193, 6, v181
	v_mov_b32_e32 v194, s6
	v_lshl_add_u32 v194, v194, 3, v193
	v_lshl_add_u32 v195, v181, 9, v183
	v_add_u32_e32 v195, 0x1000, v195
	v_mov_b32_e32 v196, s6
	v_lshl_add_u32 v196, v196, 6, v195
	v_mov_b32_e32 v4, 0
	v_mov_b32_e32 v5, 0
	v_mov_b32_e32 v6, 0
	v_mov_b32_e32 v7, 0
	v_mov_b32_e32 v8, 0
	v_mov_b32_e32 v9, 0
	v_mov_b32_e32 v10, 0
	v_mov_b32_e32 v11, 0
	v_mov_b32_e32 v12, 0
	v_mov_b32_e32 v13, 0
	v_mov_b32_e32 v14, 0
	v_mov_b32_e32 v15, 0
	v_mov_b32_e32 v16, 0
	v_mov_b32_e32 v17, 0
	v_mov_b32_e32 v18, 0
	v_mov_b32_e32 v19, 0
	s_waitcnt vmcnt(16)
	v_mfma_f32_16x16x32_bf16 v[4:7], v[52:55], v[20:23], v[4:7]
	v_mfma_f32_16x16x32_bf16 v[8:11], v[84:87], v[20:23], v[8:11]
	v_mfma_f32_16x16x32_bf16 v[4:7], v[56:59], v[24:27], v[4:7]
	v_mfma_f32_16x16x32_bf16 v[8:11], v[88:91], v[24:27], v[8:11]
	v_mfma_f32_16x16x32_bf16 v[4:7], v[60:63], v[28:31], v[4:7]
	v_mfma_f32_16x16x32_bf16 v[8:11], v[92:95], v[28:31], v[8:11]
	v_mfma_f32_16x16x32_bf16 v[4:7], v[64:67], v[32:35], v[4:7]
	v_mfma_f32_16x16x32_bf16 v[8:11], v[96:99], v[32:35], v[8:11]
	v_mfma_f32_16x16x32_bf16 v[4:7], v[68:71], v[36:39], v[4:7]
	v_mfma_f32_16x16x32_bf16 v[8:11], v[100:103], v[36:39], v[8:11]
	v_mfma_f32_16x16x32_bf16 v[4:7], v[72:75], v[40:43], v[4:7]
	v_mfma_f32_16x16x32_bf16 v[8:11], v[104:107], v[40:43], v[8:11]
	v_mfma_f32_16x16x32_bf16 v[4:7], v[76:79], v[44:47], v[4:7]
	v_mfma_f32_16x16x32_bf16 v[8:11], v[108:111], v[44:47], v[8:11]
	v_mfma_f32_16x16x32_bf16 v[4:7], v[80:83], v[48:51], v[4:7]
	v_mfma_f32_16x16x32_bf16 v[8:11], v[112:115], v[48:51], v[8:11]
	s_nop 7
	s_nop 1
	v_max3_f32 v198, v4, v5, v6
	v_max3_f32 v198, v198, v7, v8
	v_max3_f32 v198, v198, v9, v10
	v_max_f32_e32 v198, v198, v11
	s_nop 0
	ds_bpermute_b32 v197, v191, v198
	s_waitcnt lgkmcnt(0)
	v_max_f32_e32 v198, v198, v197
	s_nop 0
	ds_bpermute_b32 v197, v192, v198
	s_waitcnt lgkmcnt(0)
	v_max_f32_e32 v198, v198, v197
	v_sub_f32_e32 v4, v4, v198
	v_mul_f32_e32 v4, 0x3fb8aa3b, v4
	v_exp_f32_e32 v4, v4
	v_sub_f32_e32 v5, v5, v198
	v_mul_f32_e32 v5, 0x3fb8aa3b, v5
	v_exp_f32_e32 v5, v5
	v_sub_f32_e32 v6, v6, v198
	v_mul_f32_e32 v6, 0x3fb8aa3b, v6
	v_exp_f32_e32 v6, v6
	v_sub_f32_e32 v7, v7, v198
	v_mul_f32_e32 v7, 0x3fb8aa3b, v7
	v_exp_f32_e32 v7, v7
	v_sub_f32_e32 v8, v8, v198
	v_mul_f32_e32 v8, 0x3fb8aa3b, v8
	v_exp_f32_e32 v8, v8
	v_sub_f32_e32 v9, v9, v198
	v_mul_f32_e32 v9, 0x3fb8aa3b, v9
	v_exp_f32_e32 v9, v9
	v_sub_f32_e32 v10, v10, v198
	v_mul_f32_e32 v10, 0x3fb8aa3b, v10
	v_exp_f32_e32 v10, v10
	v_sub_f32_e32 v11, v11, v198
	v_mul_f32_e32 v11, 0x3fb8aa3b, v11
	v_exp_f32_e32 v11, v11
	s_nop 0
	v_add_f32_e32 v199, v4, v5
	v_add_f32_e32 v197, v6, v7
	v_add_f32_e32 v199, v199, v197
	v_add_f32_e32 v197, v8, v9
	v_add_f32_e32 v200, v10, v11
	v_add_f32_e32 v197, v197, v200
	v_add_f32_e32 v199, v199, v197
	s_nop 0
	ds_bpermute_b32 v197, v191, v199
	s_waitcnt lgkmcnt(0)
	v_add_f32_e32 v199, v199, v197
	s_nop 0
	ds_bpermute_b32 v197, v192, v199
	s_waitcnt lgkmcnt(0)
	v_add_f32_e32 v199, v199, v197
	v_cmp_gt_u32_e32 vcc, 16, v180
	s_and_saveexec_b64 s[8:9], vcc
	ds_write_b64 v194, v[198:199]
	s_or_b64 exec, exec, s[8:9]
	s_waitcnt lgkmcnt(0)
	s_barrier
; #define EPI_FOR_ROWS for (int ai = 0; ai < 2; ++ai) _Pragma("unroll") for (int m = 0; m < 4; ++m)
; __device__ __forceinline__ u32x4 pack8(const f32x4 a, const f32x4 b) { u32x4 w; w.x = cvt_pk_bf16(a[0], a[1]); w.y = cvt_pk_bf16(a[2], a[3]); w.z = cvt_pk_bf16(b[0], b[1]); w.w = cvt_pk_bf16(b[2], b[3]); return w; }
;     __device__ __forceinline__ void operator()(f32x4 (&acc)[2][2][4][2], const Unit& u, int wr, int wc, int fr_, int fq_, LAS unsigned char* ldsx) const {
;     ...
;         asm volatile("s_waitcnt lgkmcnt(0)" ::: "memory"); __builtin_amdgcn_s_barrier(); asm volatile("" ::: "memory");
; #pragma unroll
;         EPI_FOR_ROWS {
;             const int rl = ai * HALF + wr * 64 + m * 16 + fr;
;             const f32x2 a = X[rl * 4 + 0], b = X[rl * 4 + 1], c = X[rl * 4 + 2], d = X[rl * 4 + 3];
;             const float M = fmaxf(fmaxf(a.x, b.x), fmaxf(c.x, d.x));
;             const float Lsum = a.y * __expf(a.x - M) + b.y * __expf(b.x - M) + c.y * __expf(c.x - M) + d.y * __expf(d.x - M);
;             const float sc = __expf(mx[ai][m] - M) * __builtin_amdgcn_rcpf(Lsum);
;             if (u.nvalid >= 0 ? rl < u.nvalid : rl >= 256 + u.nvalid) {
;                 const size_t row = (size_t)u.row0 + rl;
; #pragma unroll
;                 for (int bj = 0; bj < 2; ++bj) *(u32x4*)(P + row * DM + u.col0 + bj * HALF + wc * 32 + 8 * fq) = pack8(acc[ai][bj][m][0] * sc, acc[ai][bj][m][1] * sc);
;             }
;             asm volatile("" ::: "memory");
;         }
;         asm volatile("s_waitcnt lgkmcnt(0)" ::: "memory"); __builtin_amdgcn_s_barrier(); asm volatile("" ::: "memory");
;     }
; __global__ void __launch_bounds__(512, 2) fwd_megakernel(Params p) {
;     ...
;     if constexpr (PHASE_MASK & 1024) { AttSched S{Pb, Vt, 1, G, c, 512}; EpiGen<0> E{Ob, DM, nullptr, 0, nullptr, 1.f};
;       gemm_phase<EpiGen<0>, AttSched, true>(F.lds, GemmDesc{NMEM, DM, NMEM}, S, E); }
	ds_read_b128 v[52:55], v193
	ds_read_b128 v[56:59], v193 offset:16
	ds_read_b128 v[60:63], v193 offset:32
	ds_read_b128 v[64:67], v193 offset:48
	s_waitcnt lgkmcnt(0)
	v_max3_f32 v200, v52, v54, v56
	v_max3_f32 v200, v200, v58, v60
	v_max3_f32 v200, v200, v62, v64
	v_max_f32_e32 v200, v200, v66
	v_mov_b32_e32 v201, 0
	v_sub_f32_e32 v197, v52, v200
	v_mul_f32_e32 v197, 0x3fb8aa3b, v197
	v_exp_f32_e32 v197, v197
	s_nop 0
	v_fmac_f32_e32 v201, v53, v197
	v_sub_f32_e32 v197, v54, v200
	v_mul_f32_e32 v197, 0x3fb8aa3b, v197
	v_exp_f32_e32 v197, v197
	s_nop 0
	v_fmac_f32_e32 v201, v55, v197
	v_sub_f32_e32 v197, v56, v200
	v_mul_f32_e32 v197, 0x3fb8aa3b, v197
	v_exp_f32_e32 v197, v197
	s_nop 0
	v_fmac_f32_e32 v201, v57, v197
	v_sub_f32_e32 v197, v58, v200
	v_mul_f32_e32 v197, 0x3fb8aa3b, v197
	v_exp_f32_e32 v197, v197
	s_nop 0
	v_fmac_f32_e32 v201, v59, v197
	v_sub_f32_e32 v197, v60, v200
	v_mul_f32_e32 v197, 0x3fb8aa3b, v197
	v_exp_f32_e32 v197, v197
	s_nop 0
	v_fmac_f32_e32 v201, v61, v197
	v_sub_f32_e32 v197, v62, v200
	v_mul_f32_e32 v197, 0x3fb8aa3b, v197
	v_exp_f32_e32 v197, v197
	s_nop 0
	v_fmac_f32_e32 v201, v63, v197
	v_sub_f32_e32 v197, v64, v200
	v_mul_f32_e32 v197, 0x3fb8aa3b, v197
	v_exp_f32_e32 v197, v197
	s_nop 0
	v_fmac_f32_e32 v201, v65, v197
	v_sub_f32_e32 v197, v66, v200
	v_mul_f32_e32 v197, 0x3fb8aa3b, v197
	v_exp_f32_e32 v197, v197
	s_nop 0
	v_fmac_f32_e32 v201, v67, v197
	v_sub_f32_e32 v197, v198, v200
	v_mul_f32_e32 v197, 0x3fb8aa3b, v197
	v_exp_f32_e32 v197, v197
	v_rcp_f32_e32 v184, v201
	s_nop 0
	v_mul_f32_e32 v184, v184, v197
	v_mul_f32_e32 v4, v4, v184
	v_mul_f32_e32 v5, v5, v184
	v_mul_f32_e32 v6, v6, v184
	v_mul_f32_e32 v7, v7, v184
	v_mul_f32_e32 v8, v8, v184
	v_mul_f32_e32 v9, v9, v184
	v_mul_f32_e32 v10, v10, v184
	v_mul_f32_e32 v11, v11, v184
	v_cvt_pk_bf16_f32 v68, v4, v5
	v_cvt_pk_bf16_f32 v69, v6, v7
	v_cvt_pk_bf16_f32 v70, v8, v9
	v_cvt_pk_bf16_f32 v71, v10, v11
	ds_write_b128 v196, v[68:71]
	s_waitcnt lgkmcnt(0)
	s_barrier
	ds_read_b128 v[20:23], v195
	ds_read_b128 v[24:27], v195 offset:64
	ds_read_b128 v[28:31], v195 offset:128
	ds_read_b128 v[32:35], v195 offset:192
	ds_read_b128 v[36:39], v195 offset:256
	ds_read_b128 v[40:43], v195 offset:320
	ds_read_b128 v[44:47], v195 offset:384
	ds_read_b128 v[48:51], v195 offset:448
	s_waitcnt vmcnt(0) lgkmcnt(0)
	v_mfma_f32_16x16x32_bf16 v[12:15], v[116:119], v[20:23], v[12:15]
	v_mfma_f32_16x16x32_bf16 v[16:19], v[148:151], v[20:23], v[16:19]
	v_mfma_f32_16x16x32_bf16 v[12:15], v[120:123], v[24:27], v[12:15]
	v_mfma_f32_16x16x32_bf16 v[16:19], v[152:155], v[24:27], v[16:19]
	v_mfma_f32_16x16x32_bf16 v[12:15], v[124:127], v[28:31], v[12:15]
	v_mfma_f32_16x16x32_bf16 v[16:19], v[156:159], v[28:31], v[16:19]
	v_mfma_f32_16x16x32_bf16 v[12:15], v[128:131], v[32:35], v[12:15]
	v_mfma_f32_16x16x32_bf16 v[16:19], v[160:163], v[32:35], v[16:19]
	v_mfma_f32_16x16x32_bf16 v[12:15], v[132:135], v[36:39], v[12:15]
	v_mfma_f32_16x16x32_bf16 v[16:19], v[164:167], v[36:39], v[16:19]
	v_mfma_f32_16x16x32_bf16 v[12:15], v[136:139], v[40:43], v[12:15]
	v_mfma_f32_16x16x32_bf16 v[16:19], v[168:171], v[40:43], v[16:19]
	v_mfma_f32_16x16x32_bf16 v[12:15], v[140:143], v[44:47], v[12:15]
	v_mfma_f32_16x16x32_bf16 v[16:19], v[172:175], v[44:47], v[16:19]
	v_mfma_f32_16x16x32_bf16 v[12:15], v[144:147], v[48:51], v[12:15]
	v_mfma_f32_16x16x32_bf16 v[16:19], v[176:179], v[48:51], v[16:19]
	s_nop 7
	s_nop 1
	v_cvt_pk_bf16_f32 v72, v12, v13
	v_cvt_pk_bf16_f32 v73, v14, v15
	v_cvt_pk_bf16_f32 v74, v16, v17
	v_cvt_pk_bf16_f32 v75, v18, v19
	global_store_dwordx2 v190, v[72:73], s[58:59]
	global_store_dwordx2 v190, v[74:75], s[58:59] offset:32
.Lsat_done:
	s_mov_b64 s[16:17], 0
	v_readfirstlane_b32 s20, v202
	s_branch .LBB0_1099
	s_cmp_lt_u32 s2, 0x7ffffe00
	s_cbranch_scc0 .LBB0_1097
	s_lshr_b32 s1, s2, 2
	s_lshl_b32 s0, s1, 4
	s_lshl_b32 s4, s3, 8
	s_addk_i32 s0, 0x7f10
	s_and_b32 s8, s4, 0x300
	s_add_i32 s10, s1, 2
	s_mov_b32 s4, -16
	s_cbranch_execz .LBB0_1098
	s_branch .LBB0_1099
